# no invalidate after P5: the loads that could leave stale copies of the region MERGED later overlays (attention Q in P4, GDN raw rows in P5) now bypass L1
# speedup vs baseline: 1.0027x; 1.0020x over previous
.LBB0_969:
	s_andn2_b64 vcc, exec, s[12:13]
	s_cbranch_vccnz .LBB0_986
	v_readlane_b32 s16, v255, 24
	v_lshlrev_b64 v[0:1], 9, v[130:131]
	v_readlane_b32 s17, v255, 25
	s_lshl_b32 s82, s23, 1
	v_lshlrev_b64 v[2:3], 1, v[132:133]
	v_lshl_add_u64 v[0:1], s[16:17], 0, v[0:1]
	v_lshl_add_u64 v[0:1], v[0:1], 0, s[82:83]
	v_lshl_add_u64 v[0:1], v[0:1], 0, v[2:3]
	v_readlane_b32 s10, v252, 37
	s_lshl_b32 s11, s43, 14
	global_load_dwordx4 v[34:37], v[0:1], off sc1
	global_load_dwordx4 v[38:41], v[0:1], off offset:64 sc1
	v_or_b32_e32 v0, s10, v166
	s_lshl_b32 s10, s21, 16
	s_and_b32 s11, s11, 0x8000
	s_or_b32 s12, s10, s11
	v_readlane_b32 s10, v255, 40
	v_ashrrev_i32_e32 v4, 3, v188
	v_lshlrev_b32_e32 v5, 3, v188
	s_add_u32 s10, s10, s12
	v_readlane_b32 s11, v255, 41
	v_and_b32_e32 v16, 56, v5
	v_and_b32_e32 v17, 0x78, v5
	v_ashrrev_i32_e32 v5, 31, v4
	s_addc_u32 s11, s11, 0
	v_lshlrev_b64 v[6:7], 7, v[4:5]
	v_lshl_add_u64 v[6:7], s[10:11], 0, v[6:7]
	v_lshlrev_b32_e32 v8, 1, v16
	v_lshl_add_u64 v[6:7], v[6:7], 0, v[8:9]
	s_movk_i32 s10, 0x2000
	v_readlane_b32 s13, v255, 42
	v_ashrrev_i32_e32 v10, 4, v188
	v_add_co_u32_e32 v12, vcc, s10, v6
	s_add_u32 s12, s13, s12
	v_readlane_b32 s13, v255, 43
	v_addc_co_u32_e32 v13, vcc, 0, v7, vcc
	v_ashrrev_i32_e32 v11, 31, v10
	v_add_u32_e32 v0, s22, v0
	s_addc_u32 s13, s13, 0
	global_load_dwordx4 v[42:45], v[6:7], off
	global_load_dwordx4 v[46:49], v[12:13], off
	v_lshlrev_b64 v[12:13], 9, v[10:11]
	v_ashrrev_i32_e32 v1, 31, v0
	v_lshl_add_u64 v[12:13], s[12:13], 0, v[12:13]
	v_lshlrev_b32_e32 v8, 1, v17
	v_lshl_add_u64 v[12:13], v[12:13], 0, v[8:9]
	s_movk_i32 s10, 0x4000
	v_lshlrev_b64 v[0:1], 9, v[0:1]
	v_add_co_u32_e32 v14, vcc, s10, v12
	v_lshl_add_u64 v[0:1], s[16:17], 0, v[0:1]
	s_nop 0
	v_addc_co_u32_e32 v15, vcc, 0, v13, vcc
	v_lshl_add_u64 v[0:1], v[0:1], 0, s[82:83]
	v_lshl_add_u64 v[0:1], v[0:1], 0, v[2:3]
	v_add_co_u32_e32 v2, vcc, s10, v6
	s_movk_i32 s10, 0x6000
	s_nop 0
	v_addc_co_u32_e32 v3, vcc, 0, v7, vcc
	s_mov_b64 s[12:13], 0x4000
	v_add_co_u32_e32 v6, vcc, s10, v6
	global_load_dwordx4 v[50:53], v[12:13], off
	global_load_dwordx4 v[54:57], v[14:15], off
	global_load_dwordx4 v[58:61], v[0:1], off sc1
	global_load_dwordx4 v[62:65], v[0:1], off offset:64 sc1
	v_lshl_add_u64 v[0:1], v[12:13], 0, s[12:13]
	v_addc_co_u32_e32 v7, vcc, 0, v7, vcc
	global_load_dwordx4 v[74:77], v[2:3], off
	global_load_dwordx4 v[78:81], v[6:7], off
	global_load_dwordx4 v[70:73], v[12:13], off offset:256
	global_load_dwordx4 v[66:69], v[0:1], off offset:256
	s_movk_i32 s10, 0x48
	v_mul_lo_u32 v4, v4, s10
	s_movk_i32 s10, 0x88
	v_and_b32_e32 v0, 3, v238
	v_mul_u32_u24_e32 v2, 0x110, v166
	v_and_b32_e32 v3, -16, v238
	v_mul_lo_u32 v8, v10, s10
	v_readlane_b32 s10, v254, 42
	v_lshlrev_b32_e32 v1, 2, v238
	v_lshrrev_b32_e32 v5, 2, v166
	v_add3_u32 v118, v2, v3, s10
	v_mul_u32_u24_e32 v0, 0x90, v0
	s_movk_i32 s10, 0x480
	v_mov_b32_e32 v6, v9
	v_mov_b32_e32 v7, v9
	v_xor_b32_e32 v115, 64, v1
	v_xor_b32_e32 v114, 0x80, v1
	v_add_lshl_u32 v1, v16, v4, 1
	v_add_lshl_u32 v2, v17, v8, 1
	v_mad_u32_u24 v0, v5, s10, v0
	v_mov_b32_e32 v8, v9
	v_add_u32_e32 v119, 0, v1
	v_add_u32_e32 v120, 0, v2
	v_add3_u32 v121, v0, v3, 0
	v_mov_b64_e32 v[0:1], v[6:7]
	v_mov_b64_e32 v[12:13], v[8:9]
	v_mov_b64_e32 v[16:17], v[8:9]
	v_mov_b64_e32 v[20:21], v[8:9]
	v_mov_b64_e32 v[24:25], v[8:9]
	v_mov_b64_e32 v[28:29], v[8:9]
	v_mov_b64_e32 v[32:33], v[8:9]
	v_mov_b64_e32 v[2:3], v[8:9]
	v_mov_b64_e32 v[10:11], v[6:7]
	v_mov_b64_e32 v[14:15], v[6:7]
	v_mov_b64_e32 v[18:19], v[6:7]
	v_mov_b64_e32 v[22:23], v[6:7]
	v_mov_b64_e32 v[26:27], v[6:7]
	v_mov_b64_e32 v[30:31], v[6:7]
	v_mov_b64_e32 v[4:5], v[6:7]
	s_mov_b64 s[12:13], 0
	s_mov_b64 s[16:17], -1
	v_mov_b32_e32 v116, 0
	v_mov_b32_e32 v122, 0xc4800000
	v_mov_b32_e32 v117, 0
	v_mov_b32_e32 v123, 0xc4800000
	v_mov_b64_e32 v[6:7], v[8:9]
	s_waitcnt vmcnt(0)
	ds_write_b128 v119, v[42:45]
	ds_write_b128 v119, v[46:49] offset:9216
	ds_write_b128 v120, v[50:53] offset:18432
	ds_write_b128 v120, v[54:57] offset:27136
	s_waitcnt lgkmcnt(0)
	s_barrier

.LBB0_1077:
	s_cbranch_execz .LBB0_1095
	s_add_i32 s10, s84, s34
	v_or_b32_e32 v114, s10, v177
	v_ashrrev_i32_e32 v115, 31, v114
	v_readlane_b32 s10, v255, 24
	v_lshlrev_b64 v[0:1], 9, v[114:115]
	v_readlane_b32 s11, v255, 25
	s_lshl_b32 s82, s35, 7
	v_lshlrev_b64 v[2:3], 1, v[130:131]
	v_lshl_add_u64 v[0:1], s[10:11], 0, v[0:1]
	v_lshl_add_u64 v[0:1], v[0:1], 0, s[82:83]
	v_lshl_add_u64 v[0:1], v[0:1], 0, v[2:3]
	global_load_dwordx4 v[34:37], v[0:1], off sc1
	global_load_dwordx4 v[38:41], v[0:1], off offset:64 sc1
	v_or_b32_e32 v0, s34, v177
	s_addk_i32 s81, 0x2010
	v_add_u32_e32 v0, s81, v0
	v_ashrrev_i32_e32 v1, 31, v0
	v_lshlrev_b64 v[0:1], 9, v[0:1]
	s_lshr_b32 s17, s35, 1
	v_lshl_add_u64 v[0:1], s[10:11], 0, v[0:1]
	s_lshl_b32 s19, s69, 1
	v_lshl_add_u64 v[0:1], v[0:1], 0, s[82:83]
	s_or_b32 s82, s17, s19
	s_lshl_b32 s18, s35, 6
	s_lshl_b64 s[10:11], s[82:83], 17
	v_readlane_b32 s12, v255, 46
	s_add_u32 s12, s12, s10
	v_readlane_b32 s13, v255, 47
	v_ashrrev_i32_e32 v137, 31, v136
	s_addc_u32 s13, s13, s11
	v_lshlrev_b64 v[4:5], 7, v[134:135]
	v_lshlrev_b64 v[6:7], 7, v[136:137]
	v_readlane_b32 s14, v255, 48
	v_lshl_add_u64 v[4:5], s[12:13], 0, v[4:5]
	v_lshlrev_b32_e32 v8, 1, v140
	v_lshl_add_u64 v[6:7], s[12:13], 0, v[6:7]
	v_add_u32_e32 v116, 32, v132
	s_add_u32 s14, s14, s10
	v_readlane_b32 s10, v255, 49
	v_lshl_add_u64 v[4:5], v[4:5], 0, v[8:9]
	v_lshl_add_u64 v[6:7], v[6:7], 0, v[8:9]
	v_ashrrev_i32_e32 v117, 31, v116
	s_addc_u32 s15, s10, s11
	global_load_dwordx4 v[50:53], v[4:5], off
	global_load_dwordx4 v[54:57], v[6:7], off
	v_lshlrev_b64 v[6:7], 11, v[132:133]
	v_lshlrev_b64 v[10:11], 11, v[116:117]
	v_lshl_add_u64 v[6:7], s[14:15], 0, v[6:7]
	v_lshlrev_b32_e32 v8, 1, v138
	v_lshl_add_u64 v[10:11], s[14:15], 0, v[10:11]
	v_lshl_add_u64 v[6:7], v[6:7], 0, v[8:9]
	v_lshl_add_u64 v[10:11], v[10:11], 0, v[8:9]
	v_lshl_add_u64 v[0:1], v[0:1], 0, v[2:3]
	s_movk_i32 s10, 0x4000
	global_load_dwordx4 v[62:65], v[6:7], off
	global_load_dwordx4 v[78:81], v[10:11], off
	global_load_dwordx4 v[42:45], v[0:1], off sc1
	global_load_dwordx4 v[46:49], v[0:1], off offset:64 sc1
	v_add_co_u32_e32 v0, vcc, s10, v4
	s_movk_i32 s10, 0x6000
	s_nop 0
	v_addc_co_u32_e32 v1, vcc, 0, v5, vcc
	v_add_co_u32_e32 v2, vcc, s10, v4
	v_readlane_b32 s10, v254, 42
	s_nop 0
	v_addc_co_u32_e32 v3, vcc, 0, v5, vcc
	global_load_dwordx4 v[70:73], v[0:1], off
	global_load_dwordx4 v[74:77], v[2:3], off
	global_load_dwordx4 v[66:69], v[6:7], off offset:256
	global_load_dwordx4 v[58:61], v[10:11], off offset:256
	v_add3_u32 v126, v191, v189, s10
	s_movk_i32 s10, 0x480
	v_mad_u32_u24 v5, v192, s10, v193
	v_readlane_b32 s10, v255, 52
	s_add_i32 s19, s19, s10
	s_or_b32 s82, s19, s17
	s_lshl_b64 s[20:21], s[82:83], 16
	v_readlane_b32 s10, v255, 50
	v_add_lshl_u32 v124, v140, v195, 1
	v_add_lshl_u32 v125, v138, v194, 1
	s_add_u32 s10, s10, s20
	v_readlane_b32 s11, v255, 51
	v_lshlrev_b32_e32 v4, 2, v238
	v_mov_b32_e32 v2, v9
	v_mov_b32_e32 v3, v9
	v_add_u32_e32 v6, 0, v124
	v_add_u32_e32 v7, 0, v125
	s_addc_u32 s11, s11, s21
	v_readlane_b32 s17, v255, 53
	v_mov_b32_e32 v0, v9
	v_mov_b32_e32 v1, v9
	v_xor_b32_e32 v122, 64, v4
	v_xor_b32_e32 v121, 0x80, v4
	v_add3_u32 v128, v5, v189, 0
	s_add_u32 s17, s17, s20
	v_readlane_b32 s19, v255, 54
	v_mov_b64_e32 v[12:13], v[2:3]
	v_mov_b64_e32 v[16:17], v[2:3]
	v_mov_b64_e32 v[20:21], v[2:3]
	v_mov_b64_e32 v[24:25], v[2:3]
	v_mov_b64_e32 v[28:29], v[2:3]
	v_mov_b64_e32 v[32:33], v[2:3]
	s_mov_b32 s16, 0
	s_waitcnt vmcnt(0)
	ds_write_b128 v6, v[50:53]
	ds_write_b128 v6, v[54:57] offset:9216
	ds_write_b128 v7, v[62:65] offset:18432
	ds_write_b128 v7, v[78:81] offset:27136
	v_mov_b64_e32 v[6:7], v[2:3]
	v_mov_b32_e32 v120, 0
	v_mov_b32_e32 v127, 0xc4800000
	s_addc_u32 s19, s19, s21
	v_lshlrev_b32_e32 v8, 1, v140
	v_lshlrev_b32_e32 v118, 1, v138
	v_mov_b64_e32 v[4:5], v[0:1]
	v_mov_b64_e32 v[10:11], v[0:1]
	v_mov_b64_e32 v[14:15], v[0:1]
	v_mov_b32_e32 v123, 0
	v_mov_b32_e32 v129, 0xc4800000
	v_mov_b64_e32 v[18:19], v[0:1]
	v_mov_b64_e32 v[22:23], v[0:1]
	v_mov_b64_e32 v[26:27], v[0:1]
	v_mov_b64_e32 v[30:31], v[0:1]
	s_waitcnt lgkmcnt(0)
	s_barrier
	s_cmp_gt_u32 s16, 9
	s_cbranch_scc1 .LBB0_1080

.LBB0_1155:
	s_or_b64 exec, exec, s[14:15]
	s_movk_i32 s6, 0x660
	v_cmp_gt_i32_e32 vcc, s6, v2
	s_and_saveexec_b64 s[14:15], vcc
	s_cbranch_execz .LBB0_1157
	s_add_i32 m0, s62, 0x1fc00
	s_nop 0
	global_load_lds_dwordx4 v[0:1], off sc1

.LBB0_1159:
	s_or_b64 exec, exec, s[14:15]
	s_movk_i32 s6, 0x460
	v_cmp_gt_i32_e32 vcc, s6, v2
	s_and_saveexec_b64 s[14:15], vcc
	s_cbranch_execz .LBB0_1161
	v_readlane_b32 s6, v252, 16
	s_mov_b32 m0, s6
	s_nop 0
	global_load_lds_dwordx4 v[0:1], off sc1

.LBB0_1163:
	s_or_b64 exec, exec, s[14:15]
	s_movk_i32 s6, 0x260
	v_cmp_gt_i32_e32 vcc, s6, v2
	s_and_saveexec_b64 s[14:15], vcc
	s_cbranch_execz .LBB0_1165
	v_readlane_b32 s6, v252, 17
	s_mov_b32 m0, s6
	s_nop 0
	global_load_lds_dwordx4 v[0:1], off sc1

.LBB0_1167:
	s_or_b64 exec, exec, s[12:13]
	s_movk_i32 s6, 0x60
	v_cmp_gt_i32_e32 vcc, s6, v2
	s_and_saveexec_b64 s[10:11], vcc
	s_cbranch_execz .LBB0_1169
	v_readlane_b32 s6, v252, 18
	s_mov_b32 m0, s6
	s_nop 0
	global_load_lds_dwordx4 v[0:1], off sc1

.LBB0_1185:
	s_or_b64 exec, exec, s[12:13]
	s_movk_i32 s12, 0x660
	v_cmp_gt_i32_e32 vcc, s12, v60
	s_and_saveexec_b64 s[12:13], vcc
	s_cbranch_execz .LBB0_1187
	s_add_i32 m0, s62, 0x1fc00
	s_nop 0
	global_load_lds_dwordx4 v[46:47], off sc1

.LBB0_1189:
	s_or_b64 exec, exec, s[12:13]
	s_movk_i32 s12, 0x460
	v_cmp_gt_i32_e32 vcc, s12, v60
	s_and_saveexec_b64 s[12:13], vcc
	s_cbranch_execz .LBB0_1191
	v_readlane_b32 s37, v252, 16
	s_mov_b32 m0, s37
	s_nop 0
	global_load_lds_dwordx4 v[46:47], off sc1

.LBB0_1193:
	s_or_b64 exec, exec, s[12:13]
	s_movk_i32 s12, 0x260
	v_cmp_gt_i32_e32 vcc, s12, v60
	s_and_saveexec_b64 s[12:13], vcc
	s_cbranch_execz .LBB0_1195
	v_readlane_b32 s37, v252, 17
	s_mov_b32 m0, s37
	s_nop 0
	global_load_lds_dwordx4 v[46:47], off sc1

.LBB0_1197:
	s_or_b64 exec, exec, s[12:13]
	s_movk_i32 s12, 0x60
	v_cmp_gt_i32_e32 vcc, s12, v60
	s_and_saveexec_b64 s[12:13], vcc
	s_cbranch_execz .LBB0_1199
	v_readlane_b32 s15, v252, 18
	s_mov_b32 m0, s15
	s_nop 0
	global_load_lds_dwordx4 v[46:47], off sc1
